# mid8 stack plus P15 gate GEMM epilogue rewrite: the 16 serial PUP load/wait/store rounds replaced by 16 hoisted loads and counted vmcnt(15), same arithmetic
# speedup vs baseline: 1.0009x; 1.0009x over previous
; __device__ __forceinline__ unsigned cvt_pk_bf16(float lo, float hi) { unsigned r; asm volatile("v_cvt_pk_bf16_f32 %0, %1, %2" : "=v"(r) : "v"(lo), "v"(hi)); return r; }
; __device__ __forceinline__ f32x4 sigm4(f32x4 v) { return (f32x4){sigm(v[0]), sigm(v[1]), sigm(v[2]), sigm(v[3])}; }
; __device__ __forceinline__ void unpack8(u32x4 w, f32x4& lo, f32x4& hi) { lo = (f32x4){bfl(w.x), bfh(w.x), bfl(w.y), bfh(w.y)}; hi = (f32x4){bfl(w.z), bfh(w.z), bfl(w.w), bfh(w.w)}; }
; __device__ __forceinline__ float sigm(float x) { return __builtin_amdgcn_rcpf(1.0f + __expf(-x)); }
;     __device__ __forceinline__ void operator()(const f32x4 (&acc)[2][2][4][2], const Unit& u, int wr, int wc, int fr, int fq) const {
;         const int row0 = u.pm * BM + wr * 64 + fr, col0 = u.pn * BM + wc * 32 + 8 * fq;
; #pragma unroll
;         for (int ai = 0; ai < 2; ++ai)
; #pragma unroll
;             for (int m = 0; m < 4; ++m) { const size_t ro = (size_t)(row0 + ai * HALF + m * 16) * D + col0;
; #pragma unroll
;                 for (int bj = 0; bj < 2; ++bj) { const u32x4 pw = *(const u32x4*)(PUP + ro + bj * HALF); f32x4 p0, p1; unpack8(pw, p0, p1);
;                     const f32x4 v0 = sigm4(acc[ai][bj][m][0]) * p0, v1 = sigm4(acc[ai][bj][m][1]) * p1;
;                     u32x4 w; w.x = cvt_pk_bf16(v0[0], v0[1]); w.y = cvt_pk_bf16(v0[2], v0[3]); w.z = cvt_pk_bf16(v1[0], v1[1]); w.w = cvt_pk_bf16(v1[2], v1[3]);
;                     *(u32x4*)(T + ro + bj * HALF) = w; }
;                 asm volatile("" ::: "memory"); }
.LBB0_1823:
	s_andn2_b64 vcc, exec, s[0:1]
	s_mov_b64 s[0:1], -1
	v_lshl_add_u32 v242, s30, 8, v152
	v_lshl_or_b32 v243, s53, 8, v154
	v_lshl_add_u32 v242, v242, 11, v243
	v_lshlrev_b32_e32 v158, 1, v242
	v_add_u32_e32 v159, 0x10000, v158
	v_add_u32_e32 v160, 0x20000, v158
	v_add_u32_e32 v161, 0x30000, v158
	v_add_u32_e32 v162, 0x80000, v158
	v_add_u32_e32 v163, 0x90000, v158
	v_add_u32_e32 v164, 0xa0000, v158
	v_add_u32_e32 v165, 0xb0000, v158
	global_load_dwordx4 v[166:169], v158, s[10:11]
	global_load_dwordx4 v[170:173], v158, s[10:11] offset:256
	global_load_dwordx4 v[174:177], v159, s[10:11]
	global_load_dwordx4 v[178:181], v159, s[10:11] offset:256
	global_load_dwordx4 v[182:185], v160, s[10:11]
	global_load_dwordx4 v[186:189], v160, s[10:11] offset:256
	global_load_dwordx4 v[190:193], v161, s[10:11]
	global_load_dwordx4 v[194:197], v161, s[10:11] offset:256
	global_load_dwordx4 v[198:201], v162, s[10:11]
	global_load_dwordx4 v[202:205], v162, s[10:11] offset:256
	global_load_dwordx4 v[206:209], v163, s[10:11]
	global_load_dwordx4 v[210:213], v163, s[10:11] offset:256
	global_load_dwordx4 v[214:217], v164, s[10:11]
	global_load_dwordx4 v[218:221], v164, s[10:11] offset:256
	global_load_dwordx4 v[222:225], v165, s[10:11]
	global_load_dwordx4 v[226:229], v165, s[10:11] offset:256
	v_mul_f32_e32 v126, 0xbfb8aa3b, v126
	v_mul_f32_e32 v127, 0xbfb8aa3b, v127
	v_mul_f32_e32 v128, 0xbfb8aa3b, v128
	v_mul_f32_e32 v129, 0xbfb8aa3b, v129
	v_mul_f32_e32 v122, 0xbfb8aa3b, v122
	v_mul_f32_e32 v123, 0xbfb8aa3b, v123
	v_mul_f32_e32 v124, 0xbfb8aa3b, v124
	v_mul_f32_e32 v125, 0xbfb8aa3b, v125
	v_exp_f32_e32 v126, v126
	v_exp_f32_e32 v127, v127
	v_exp_f32_e32 v128, v128
	v_exp_f32_e32 v129, v129
	v_exp_f32_e32 v122, v122
	v_exp_f32_e32 v123, v123
	v_exp_f32_e32 v124, v124
	v_exp_f32_e32 v125, v125
	v_add_f32_e32 v126, 1.0, v126
	v_add_f32_e32 v127, 1.0, v127
	v_add_f32_e32 v128, 1.0, v128
	v_add_f32_e32 v129, 1.0, v129
	v_add_f32_e32 v122, 1.0, v122
	v_add_f32_e32 v123, 1.0, v123
	v_add_f32_e32 v124, 1.0, v124
	v_add_f32_e32 v125, 1.0, v125
	v_rcp_f32_e32 v126, v126
	v_rcp_f32_e32 v127, v127
	v_rcp_f32_e32 v128, v128
	v_rcp_f32_e32 v129, v129
	v_rcp_f32_e32 v122, v122
	v_rcp_f32_e32 v123, v123
	v_rcp_f32_e32 v124, v124
	v_rcp_f32_e32 v125, v125
	s_waitcnt vmcnt(15)
	v_lshlrev_b32_e32 v230, 16, v166
	v_and_b32_e32 v231, 0xffff0000, v166
	v_lshlrev_b32_e32 v232, 16, v167
	v_and_b32_e32 v233, 0xffff0000, v167
	v_lshlrev_b32_e32 v234, 16, v168
	v_and_b32_e32 v235, 0xffff0000, v168
	v_lshlrev_b32_e32 v236, 16, v169
	v_and_b32_e32 v237, 0xffff0000, v169
	v_mul_f32_e32 v126, v126, v230
	v_mul_f32_e32 v127, v127, v231
	v_mul_f32_e32 v128, v128, v232
	v_mul_f32_e32 v129, v129, v233
	v_mul_f32_e32 v122, v122, v234
	v_mul_f32_e32 v123, v123, v235
	v_mul_f32_e32 v124, v124, v236
	v_mul_f32_e32 v125, v125, v237
	v_cvt_pk_bf16_f32 v238, v126, v127
	v_cvt_pk_bf16_f32 v239, v128, v129
	v_cvt_pk_bf16_f32 v240, v122, v123
	v_cvt_pk_bf16_f32 v241, v124, v125
	global_store_dwordx4 v158, v[238:241], s[86:87]
	v_mul_f32_e32 v118, 0xbfb8aa3b, v118
	v_mul_f32_e32 v119, 0xbfb8aa3b, v119
	v_mul_f32_e32 v120, 0xbfb8aa3b, v120
	v_mul_f32_e32 v121, 0xbfb8aa3b, v121
	v_mul_f32_e32 v114, 0xbfb8aa3b, v114
	v_mul_f32_e32 v115, 0xbfb8aa3b, v115
	v_mul_f32_e32 v116, 0xbfb8aa3b, v116
	v_mul_f32_e32 v117, 0xbfb8aa3b, v117
	v_exp_f32_e32 v118, v118
	v_exp_f32_e32 v119, v119
	v_exp_f32_e32 v120, v120
	v_exp_f32_e32 v121, v121
	v_exp_f32_e32 v114, v114
	v_exp_f32_e32 v115, v115
	v_exp_f32_e32 v116, v116
	v_exp_f32_e32 v117, v117
	v_add_f32_e32 v118, 1.0, v118
	v_add_f32_e32 v119, 1.0, v119
	v_add_f32_e32 v120, 1.0, v120
	v_add_f32_e32 v121, 1.0, v121
	v_add_f32_e32 v114, 1.0, v114
	v_add_f32_e32 v115, 1.0, v115
	v_add_f32_e32 v116, 1.0, v116
	v_add_f32_e32 v117, 1.0, v117
	v_rcp_f32_e32 v118, v118
	v_rcp_f32_e32 v119, v119
	v_rcp_f32_e32 v120, v120
	v_rcp_f32_e32 v121, v121
	v_rcp_f32_e32 v114, v114
	v_rcp_f32_e32 v115, v115
	v_rcp_f32_e32 v116, v116
	v_rcp_f32_e32 v117, v117
	s_waitcnt vmcnt(15)
	v_lshlrev_b32_e32 v230, 16, v170
	v_and_b32_e32 v231, 0xffff0000, v170
	v_lshlrev_b32_e32 v232, 16, v171
	v_and_b32_e32 v233, 0xffff0000, v171
	v_lshlrev_b32_e32 v234, 16, v172
	v_and_b32_e32 v235, 0xffff0000, v172
	v_lshlrev_b32_e32 v236, 16, v173
	v_and_b32_e32 v237, 0xffff0000, v173
	v_mul_f32_e32 v118, v118, v230
	v_mul_f32_e32 v119, v119, v231
	v_mul_f32_e32 v120, v120, v232
	v_mul_f32_e32 v121, v121, v233
	v_mul_f32_e32 v114, v114, v234
	v_mul_f32_e32 v115, v115, v235
	v_mul_f32_e32 v116, v116, v236
	v_mul_f32_e32 v117, v117, v237
	v_cvt_pk_bf16_f32 v238, v118, v119
	v_cvt_pk_bf16_f32 v239, v120, v121
	v_cvt_pk_bf16_f32 v240, v114, v115
	v_cvt_pk_bf16_f32 v241, v116, v117
	global_store_dwordx4 v158, v[238:241], s[86:87] offset:256
	v_mul_f32_e32 v110, 0xbfb8aa3b, v110
	v_mul_f32_e32 v111, 0xbfb8aa3b, v111
	v_mul_f32_e32 v112, 0xbfb8aa3b, v112
	v_mul_f32_e32 v113, 0xbfb8aa3b, v113
	v_mul_f32_e32 v106, 0xbfb8aa3b, v106
	v_mul_f32_e32 v107, 0xbfb8aa3b, v107
	v_mul_f32_e32 v108, 0xbfb8aa3b, v108
	v_mul_f32_e32 v109, 0xbfb8aa3b, v109
	v_exp_f32_e32 v110, v110
	v_exp_f32_e32 v111, v111
	v_exp_f32_e32 v112, v112
	v_exp_f32_e32 v113, v113
	v_exp_f32_e32 v106, v106
	v_exp_f32_e32 v107, v107
	v_exp_f32_e32 v108, v108
	v_exp_f32_e32 v109, v109
	v_add_f32_e32 v110, 1.0, v110
	v_add_f32_e32 v111, 1.0, v111
	v_add_f32_e32 v112, 1.0, v112
	v_add_f32_e32 v113, 1.0, v113
	v_add_f32_e32 v106, 1.0, v106
	v_add_f32_e32 v107, 1.0, v107
	v_add_f32_e32 v108, 1.0, v108
	v_add_f32_e32 v109, 1.0, v109
	v_rcp_f32_e32 v110, v110
	v_rcp_f32_e32 v111, v111
	v_rcp_f32_e32 v112, v112
	v_rcp_f32_e32 v113, v113
	v_rcp_f32_e32 v106, v106
	v_rcp_f32_e32 v107, v107
	v_rcp_f32_e32 v108, v108
	v_rcp_f32_e32 v109, v109
	s_waitcnt vmcnt(15)
; __device__ __forceinline__ unsigned cvt_pk_bf16(float lo, float hi) { unsigned r; asm volatile("v_cvt_pk_bf16_f32 %0, %1, %2" : "=v"(r) : "v"(lo), "v"(hi)); return r; }
; __device__ __forceinline__ f32x4 sigm4(f32x4 v) { return (f32x4){sigm(v[0]), sigm(v[1]), sigm(v[2]), sigm(v[3])}; }
; __device__ __forceinline__ void unpack8(u32x4 w, f32x4& lo, f32x4& hi) { lo = (f32x4){bfl(w.x), bfh(w.x), bfl(w.y), bfh(w.y)}; hi = (f32x4){bfl(w.z), bfh(w.z), bfl(w.w), bfh(w.w)}; }
; __device__ __forceinline__ float sigm(float x) { return __builtin_amdgcn_rcpf(1.0f + __expf(-x)); }
;     __device__ __forceinline__ void operator()(const f32x4 (&acc)[2][2][4][2], const Unit& u, int wr, int wc, int fr, int fq) const {
;     ...
;             for (int m = 0; m < 4; ++m) { const size_t ro = (size_t)(row0 + ai * HALF + m * 16) * D + col0;
; #pragma unroll
;                 for (int bj = 0; bj < 2; ++bj) { const u32x4 pw = *(const u32x4*)(PUP + ro + bj * HALF); f32x4 p0, p1; unpack8(pw, p0, p1);
;                     const f32x4 v0 = sigm4(acc[ai][bj][m][0]) * p0, v1 = sigm4(acc[ai][bj][m][1]) * p1;
;                     u32x4 w; w.x = cvt_pk_bf16(v0[0], v0[1]); w.y = cvt_pk_bf16(v0[2], v0[3]); w.z = cvt_pk_bf16(v1[0], v1[1]); w.w = cvt_pk_bf16(v1[2], v1[3]);
;                     *(u32x4*)(T + ro + bj * HALF) = w; }
	v_lshlrev_b32_e32 v230, 16, v174
	v_and_b32_e32 v231, 0xffff0000, v174
	v_lshlrev_b32_e32 v232, 16, v175
	v_and_b32_e32 v233, 0xffff0000, v175
	v_lshlrev_b32_e32 v234, 16, v176
	v_and_b32_e32 v235, 0xffff0000, v176
	v_lshlrev_b32_e32 v236, 16, v177
	v_and_b32_e32 v237, 0xffff0000, v177
	v_mul_f32_e32 v110, v110, v230
	v_mul_f32_e32 v111, v111, v231
	v_mul_f32_e32 v112, v112, v232
	v_mul_f32_e32 v113, v113, v233
	v_mul_f32_e32 v106, v106, v234
	v_mul_f32_e32 v107, v107, v235
	v_mul_f32_e32 v108, v108, v236
	v_mul_f32_e32 v109, v109, v237
	v_cvt_pk_bf16_f32 v238, v110, v111
	v_cvt_pk_bf16_f32 v239, v112, v113
	v_cvt_pk_bf16_f32 v240, v106, v107
	v_cvt_pk_bf16_f32 v241, v108, v109
	global_store_dwordx4 v159, v[238:241], s[86:87]
	v_mul_f32_e32 v102, 0xbfb8aa3b, v102
	v_mul_f32_e32 v103, 0xbfb8aa3b, v103
	v_mul_f32_e32 v104, 0xbfb8aa3b, v104
	v_mul_f32_e32 v105, 0xbfb8aa3b, v105
	v_mul_f32_e32 v98, 0xbfb8aa3b, v98
	v_mul_f32_e32 v99, 0xbfb8aa3b, v99
	v_mul_f32_e32 v100, 0xbfb8aa3b, v100
	v_mul_f32_e32 v101, 0xbfb8aa3b, v101
	v_exp_f32_e32 v102, v102
	v_exp_f32_e32 v103, v103
	v_exp_f32_e32 v104, v104
	v_exp_f32_e32 v105, v105
	v_exp_f32_e32 v98, v98
	v_exp_f32_e32 v99, v99
	v_exp_f32_e32 v100, v100
	v_exp_f32_e32 v101, v101
	v_add_f32_e32 v102, 1.0, v102
	v_add_f32_e32 v103, 1.0, v103
	v_add_f32_e32 v104, 1.0, v104
	v_add_f32_e32 v105, 1.0, v105
	v_add_f32_e32 v98, 1.0, v98
	v_add_f32_e32 v99, 1.0, v99
	v_add_f32_e32 v100, 1.0, v100
	v_add_f32_e32 v101, 1.0, v101
	v_rcp_f32_e32 v102, v102
	v_rcp_f32_e32 v103, v103
	v_rcp_f32_e32 v104, v104
	v_rcp_f32_e32 v105, v105
	v_rcp_f32_e32 v98, v98
	v_rcp_f32_e32 v99, v99
	v_rcp_f32_e32 v100, v100
	v_rcp_f32_e32 v101, v101
	s_waitcnt vmcnt(15)
	v_lshlrev_b32_e32 v230, 16, v178
	v_and_b32_e32 v231, 0xffff0000, v178
	v_lshlrev_b32_e32 v232, 16, v179
	v_and_b32_e32 v233, 0xffff0000, v179
	v_lshlrev_b32_e32 v234, 16, v180
	v_and_b32_e32 v235, 0xffff0000, v180
	v_lshlrev_b32_e32 v236, 16, v181
	v_and_b32_e32 v237, 0xffff0000, v181
	v_mul_f32_e32 v102, v102, v230
	v_mul_f32_e32 v103, v103, v231
	v_mul_f32_e32 v104, v104, v232
	v_mul_f32_e32 v105, v105, v233
	v_mul_f32_e32 v98, v98, v234
	v_mul_f32_e32 v99, v99, v235
	v_mul_f32_e32 v100, v100, v236
	v_mul_f32_e32 v101, v101, v237
	v_cvt_pk_bf16_f32 v238, v102, v103
	v_cvt_pk_bf16_f32 v239, v104, v105
	v_cvt_pk_bf16_f32 v240, v98, v99
	v_cvt_pk_bf16_f32 v241, v100, v101
	global_store_dwordx4 v159, v[238:241], s[86:87] offset:256
	v_mul_f32_e32 v94, 0xbfb8aa3b, v94
	v_mul_f32_e32 v95, 0xbfb8aa3b, v95
	v_mul_f32_e32 v96, 0xbfb8aa3b, v96
	v_mul_f32_e32 v97, 0xbfb8aa3b, v97
	v_mul_f32_e32 v90, 0xbfb8aa3b, v90
	v_mul_f32_e32 v91, 0xbfb8aa3b, v91
	v_mul_f32_e32 v92, 0xbfb8aa3b, v92
	v_mul_f32_e32 v93, 0xbfb8aa3b, v93
	v_exp_f32_e32 v94, v94
	v_exp_f32_e32 v95, v95
	v_exp_f32_e32 v96, v96
	v_exp_f32_e32 v97, v97
	v_exp_f32_e32 v90, v90
	v_exp_f32_e32 v91, v91
	v_exp_f32_e32 v92, v92
	v_exp_f32_e32 v93, v93
	v_add_f32_e32 v94, 1.0, v94
	v_add_f32_e32 v95, 1.0, v95
	v_add_f32_e32 v96, 1.0, v96
	v_add_f32_e32 v97, 1.0, v97
	v_add_f32_e32 v90, 1.0, v90
	v_add_f32_e32 v91, 1.0, v91
	v_add_f32_e32 v92, 1.0, v92
	v_add_f32_e32 v93, 1.0, v93
	v_rcp_f32_e32 v94, v94
	v_rcp_f32_e32 v95, v95
	v_rcp_f32_e32 v96, v96
	v_rcp_f32_e32 v97, v97
	v_rcp_f32_e32 v90, v90
	v_rcp_f32_e32 v91, v91
	v_rcp_f32_e32 v92, v92
	v_rcp_f32_e32 v93, v93
	s_waitcnt vmcnt(15)
	v_lshlrev_b32_e32 v230, 16, v182
	v_and_b32_e32 v231, 0xffff0000, v182
	v_lshlrev_b32_e32 v232, 16, v183
	v_and_b32_e32 v233, 0xffff0000, v183
	v_lshlrev_b32_e32 v234, 16, v184
	v_and_b32_e32 v235, 0xffff0000, v184
	v_lshlrev_b32_e32 v236, 16, v185
	v_and_b32_e32 v237, 0xffff0000, v185
	v_mul_f32_e32 v94, v94, v230
	v_mul_f32_e32 v95, v95, v231
	v_mul_f32_e32 v96, v96, v232
	v_mul_f32_e32 v97, v97, v233
	v_mul_f32_e32 v90, v90, v234
	v_mul_f32_e32 v91, v91, v235
	v_mul_f32_e32 v92, v92, v236
	v_mul_f32_e32 v93, v93, v237
	v_cvt_pk_bf16_f32 v238, v94, v95
	v_cvt_pk_bf16_f32 v239, v96, v97
	v_cvt_pk_bf16_f32 v240, v90, v91
	v_cvt_pk_bf16_f32 v241, v92, v93
	global_store_dwordx4 v160, v[238:241], s[86:87]
	v_mul_f32_e32 v86, 0xbfb8aa3b, v86
	v_mul_f32_e32 v87, 0xbfb8aa3b, v87
	v_mul_f32_e32 v88, 0xbfb8aa3b, v88
	v_mul_f32_e32 v89, 0xbfb8aa3b, v89
	v_mul_f32_e32 v82, 0xbfb8aa3b, v82
	v_mul_f32_e32 v83, 0xbfb8aa3b, v83
	v_mul_f32_e32 v84, 0xbfb8aa3b, v84
	v_mul_f32_e32 v85, 0xbfb8aa3b, v85
	v_exp_f32_e32 v86, v86
	v_exp_f32_e32 v87, v87
	v_exp_f32_e32 v88, v88
	v_exp_f32_e32 v89, v89
	v_exp_f32_e32 v82, v82
	v_exp_f32_e32 v83, v83
	v_exp_f32_e32 v84, v84
	v_exp_f32_e32 v85, v85
	v_add_f32_e32 v86, 1.0, v86
	v_add_f32_e32 v87, 1.0, v87
	v_add_f32_e32 v88, 1.0, v88
	v_add_f32_e32 v89, 1.0, v89
	v_add_f32_e32 v82, 1.0, v82
	v_add_f32_e32 v83, 1.0, v83
	v_add_f32_e32 v84, 1.0, v84
	v_add_f32_e32 v85, 1.0, v85
	v_rcp_f32_e32 v86, v86
	v_rcp_f32_e32 v87, v87
	v_rcp_f32_e32 v88, v88
	v_rcp_f32_e32 v89, v89
	v_rcp_f32_e32 v82, v82
	v_rcp_f32_e32 v83, v83
	v_rcp_f32_e32 v84, v84
	v_rcp_f32_e32 v85, v85
	s_waitcnt vmcnt(15)
; __device__ __forceinline__ unsigned cvt_pk_bf16(float lo, float hi) { unsigned r; asm volatile("v_cvt_pk_bf16_f32 %0, %1, %2" : "=v"(r) : "v"(lo), "v"(hi)); return r; }
; __device__ __forceinline__ f32x4 sigm4(f32x4 v) { return (f32x4){sigm(v[0]), sigm(v[1]), sigm(v[2]), sigm(v[3])}; }
; __device__ __forceinline__ void unpack8(u32x4 w, f32x4& lo, f32x4& hi) { lo = (f32x4){bfl(w.x), bfh(w.x), bfl(w.y), bfh(w.y)}; hi = (f32x4){bfl(w.z), bfh(w.z), bfl(w.w), bfh(w.w)}; }
; __device__ __forceinline__ float sigm(float x) { return __builtin_amdgcn_rcpf(1.0f + __expf(-x)); }
;     __device__ __forceinline__ void operator()(const f32x4 (&acc)[2][2][4][2], const Unit& u, int wr, int wc, int fr, int fq) const {
;     ...
;             for (int m = 0; m < 4; ++m) { const size_t ro = (size_t)(row0 + ai * HALF + m * 16) * D + col0;
; #pragma unroll
;                 for (int bj = 0; bj < 2; ++bj) { const u32x4 pw = *(const u32x4*)(PUP + ro + bj * HALF); f32x4 p0, p1; unpack8(pw, p0, p1);
;                     const f32x4 v0 = sigm4(acc[ai][bj][m][0]) * p0, v1 = sigm4(acc[ai][bj][m][1]) * p1;
;                     u32x4 w; w.x = cvt_pk_bf16(v0[0], v0[1]); w.y = cvt_pk_bf16(v0[2], v0[3]); w.z = cvt_pk_bf16(v1[0], v1[1]); w.w = cvt_pk_bf16(v1[2], v1[3]);
;                     *(u32x4*)(T + ro + bj * HALF) = w; }
	v_lshlrev_b32_e32 v230, 16, v186
	v_and_b32_e32 v231, 0xffff0000, v186
	v_lshlrev_b32_e32 v232, 16, v187
	v_and_b32_e32 v233, 0xffff0000, v187
	v_lshlrev_b32_e32 v234, 16, v188
	v_and_b32_e32 v235, 0xffff0000, v188
	v_lshlrev_b32_e32 v236, 16, v189
	v_and_b32_e32 v237, 0xffff0000, v189
	v_mul_f32_e32 v86, v86, v230
	v_mul_f32_e32 v87, v87, v231
	v_mul_f32_e32 v88, v88, v232
	v_mul_f32_e32 v89, v89, v233
	v_mul_f32_e32 v82, v82, v234
	v_mul_f32_e32 v83, v83, v235
	v_mul_f32_e32 v84, v84, v236
	v_mul_f32_e32 v85, v85, v237
	v_cvt_pk_bf16_f32 v238, v86, v87
	v_cvt_pk_bf16_f32 v239, v88, v89
	v_cvt_pk_bf16_f32 v240, v82, v83
	v_cvt_pk_bf16_f32 v241, v84, v85
	global_store_dwordx4 v160, v[238:241], s[86:87] offset:256
	v_mul_f32_e32 v78, 0xbfb8aa3b, v78
	v_mul_f32_e32 v79, 0xbfb8aa3b, v79
	v_mul_f32_e32 v80, 0xbfb8aa3b, v80
	v_mul_f32_e32 v81, 0xbfb8aa3b, v81
	v_mul_f32_e32 v74, 0xbfb8aa3b, v74
	v_mul_f32_e32 v75, 0xbfb8aa3b, v75
	v_mul_f32_e32 v76, 0xbfb8aa3b, v76
	v_mul_f32_e32 v77, 0xbfb8aa3b, v77
	v_exp_f32_e32 v78, v78
	v_exp_f32_e32 v79, v79
	v_exp_f32_e32 v80, v80
	v_exp_f32_e32 v81, v81
	v_exp_f32_e32 v74, v74
	v_exp_f32_e32 v75, v75
	v_exp_f32_e32 v76, v76
	v_exp_f32_e32 v77, v77
	v_add_f32_e32 v78, 1.0, v78
	v_add_f32_e32 v79, 1.0, v79
	v_add_f32_e32 v80, 1.0, v80
	v_add_f32_e32 v81, 1.0, v81
	v_add_f32_e32 v74, 1.0, v74
	v_add_f32_e32 v75, 1.0, v75
	v_add_f32_e32 v76, 1.0, v76
	v_add_f32_e32 v77, 1.0, v77
	v_rcp_f32_e32 v78, v78
	v_rcp_f32_e32 v79, v79
	v_rcp_f32_e32 v80, v80
	v_rcp_f32_e32 v81, v81
	v_rcp_f32_e32 v74, v74
	v_rcp_f32_e32 v75, v75
	v_rcp_f32_e32 v76, v76
	v_rcp_f32_e32 v77, v77
	s_waitcnt vmcnt(15)
	v_lshlrev_b32_e32 v230, 16, v190
	v_and_b32_e32 v231, 0xffff0000, v190
	v_lshlrev_b32_e32 v232, 16, v191
	v_and_b32_e32 v233, 0xffff0000, v191
	v_lshlrev_b32_e32 v234, 16, v192
	v_and_b32_e32 v235, 0xffff0000, v192
	v_lshlrev_b32_e32 v236, 16, v193
	v_and_b32_e32 v237, 0xffff0000, v193
	v_mul_f32_e32 v78, v78, v230
	v_mul_f32_e32 v79, v79, v231
	v_mul_f32_e32 v80, v80, v232
	v_mul_f32_e32 v81, v81, v233
	v_mul_f32_e32 v74, v74, v234
	v_mul_f32_e32 v75, v75, v235
	v_mul_f32_e32 v76, v76, v236
	v_mul_f32_e32 v77, v77, v237
	v_cvt_pk_bf16_f32 v238, v78, v79
	v_cvt_pk_bf16_f32 v239, v80, v81
	v_cvt_pk_bf16_f32 v240, v74, v75
	v_cvt_pk_bf16_f32 v241, v76, v77
	global_store_dwordx4 v161, v[238:241], s[86:87]
	v_mul_f32_e32 v70, 0xbfb8aa3b, v70
	v_mul_f32_e32 v71, 0xbfb8aa3b, v71
	v_mul_f32_e32 v72, 0xbfb8aa3b, v72
	v_mul_f32_e32 v73, 0xbfb8aa3b, v73
	v_mul_f32_e32 v66, 0xbfb8aa3b, v66
	v_mul_f32_e32 v67, 0xbfb8aa3b, v67
	v_mul_f32_e32 v68, 0xbfb8aa3b, v68
	v_mul_f32_e32 v69, 0xbfb8aa3b, v69
	v_exp_f32_e32 v70, v70
	v_exp_f32_e32 v71, v71
	v_exp_f32_e32 v72, v72
	v_exp_f32_e32 v73, v73
	v_exp_f32_e32 v66, v66
	v_exp_f32_e32 v67, v67
	v_exp_f32_e32 v68, v68
	v_exp_f32_e32 v69, v69
	v_add_f32_e32 v70, 1.0, v70
	v_add_f32_e32 v71, 1.0, v71
	v_add_f32_e32 v72, 1.0, v72
	v_add_f32_e32 v73, 1.0, v73
	v_add_f32_e32 v66, 1.0, v66
	v_add_f32_e32 v67, 1.0, v67
	v_add_f32_e32 v68, 1.0, v68
	v_add_f32_e32 v69, 1.0, v69
	v_rcp_f32_e32 v70, v70
	v_rcp_f32_e32 v71, v71
	v_rcp_f32_e32 v72, v72
	v_rcp_f32_e32 v73, v73
	v_rcp_f32_e32 v66, v66
	v_rcp_f32_e32 v67, v67
	v_rcp_f32_e32 v68, v68
	v_rcp_f32_e32 v69, v69
	s_waitcnt vmcnt(15)
	v_lshlrev_b32_e32 v230, 16, v194
	v_and_b32_e32 v231, 0xffff0000, v194
	v_lshlrev_b32_e32 v232, 16, v195
	v_and_b32_e32 v233, 0xffff0000, v195
	v_lshlrev_b32_e32 v234, 16, v196
	v_and_b32_e32 v235, 0xffff0000, v196
	v_lshlrev_b32_e32 v236, 16, v197
	v_and_b32_e32 v237, 0xffff0000, v197
	v_mul_f32_e32 v70, v70, v230
	v_mul_f32_e32 v71, v71, v231
	v_mul_f32_e32 v72, v72, v232
	v_mul_f32_e32 v73, v73, v233
	v_mul_f32_e32 v66, v66, v234
	v_mul_f32_e32 v67, v67, v235
	v_mul_f32_e32 v68, v68, v236
	v_mul_f32_e32 v69, v69, v237
	v_cvt_pk_bf16_f32 v238, v70, v71
	v_cvt_pk_bf16_f32 v239, v72, v73
	v_cvt_pk_bf16_f32 v240, v66, v67
	v_cvt_pk_bf16_f32 v241, v68, v69
	global_store_dwordx4 v161, v[238:241], s[86:87] offset:256
	v_mul_f32_e32 v62, 0xbfb8aa3b, v62
	v_mul_f32_e32 v63, 0xbfb8aa3b, v63
	v_mul_f32_e32 v64, 0xbfb8aa3b, v64
	v_mul_f32_e32 v65, 0xbfb8aa3b, v65
	v_mul_f32_e32 v58, 0xbfb8aa3b, v58
	v_mul_f32_e32 v59, 0xbfb8aa3b, v59
	v_mul_f32_e32 v60, 0xbfb8aa3b, v60
	v_mul_f32_e32 v61, 0xbfb8aa3b, v61
	v_exp_f32_e32 v62, v62
	v_exp_f32_e32 v63, v63
	v_exp_f32_e32 v64, v64
	v_exp_f32_e32 v65, v65
	v_exp_f32_e32 v58, v58
	v_exp_f32_e32 v59, v59
	v_exp_f32_e32 v60, v60
	v_exp_f32_e32 v61, v61
	v_add_f32_e32 v62, 1.0, v62
	v_add_f32_e32 v63, 1.0, v63
	v_add_f32_e32 v64, 1.0, v64
	v_add_f32_e32 v65, 1.0, v65
	v_add_f32_e32 v58, 1.0, v58
	v_add_f32_e32 v59, 1.0, v59
	v_add_f32_e32 v60, 1.0, v60
	v_add_f32_e32 v61, 1.0, v61
	v_rcp_f32_e32 v62, v62
	v_rcp_f32_e32 v63, v63
	v_rcp_f32_e32 v64, v64
	v_rcp_f32_e32 v65, v65
	v_rcp_f32_e32 v58, v58
	v_rcp_f32_e32 v59, v59
	v_rcp_f32_e32 v60, v60
	v_rcp_f32_e32 v61, v61
	s_waitcnt vmcnt(15)
; __device__ __forceinline__ unsigned cvt_pk_bf16(float lo, float hi) { unsigned r; asm volatile("v_cvt_pk_bf16_f32 %0, %1, %2" : "=v"(r) : "v"(lo), "v"(hi)); return r; }
; __device__ __forceinline__ f32x4 sigm4(f32x4 v) { return (f32x4){sigm(v[0]), sigm(v[1]), sigm(v[2]), sigm(v[3])}; }
; __device__ __forceinline__ void unpack8(u32x4 w, f32x4& lo, f32x4& hi) { lo = (f32x4){bfl(w.x), bfh(w.x), bfl(w.y), bfh(w.y)}; hi = (f32x4){bfl(w.z), bfh(w.z), bfl(w.w), bfh(w.w)}; }
; __device__ __forceinline__ float sigm(float x) { return __builtin_amdgcn_rcpf(1.0f + __expf(-x)); }
;     __device__ __forceinline__ void operator()(const f32x4 (&acc)[2][2][4][2], const Unit& u, int wr, int wc, int fr, int fq) const {
;     ...
;             for (int m = 0; m < 4; ++m) { const size_t ro = (size_t)(row0 + ai * HALF + m * 16) * D + col0;
; #pragma unroll
;                 for (int bj = 0; bj < 2; ++bj) { const u32x4 pw = *(const u32x4*)(PUP + ro + bj * HALF); f32x4 p0, p1; unpack8(pw, p0, p1);
;                     const f32x4 v0 = sigm4(acc[ai][bj][m][0]) * p0, v1 = sigm4(acc[ai][bj][m][1]) * p1;
;                     u32x4 w; w.x = cvt_pk_bf16(v0[0], v0[1]); w.y = cvt_pk_bf16(v0[2], v0[3]); w.z = cvt_pk_bf16(v1[0], v1[1]); w.w = cvt_pk_bf16(v1[2], v1[3]);
;                     *(u32x4*)(T + ro + bj * HALF) = w; }
	v_lshlrev_b32_e32 v230, 16, v198
	v_and_b32_e32 v231, 0xffff0000, v198
	v_lshlrev_b32_e32 v232, 16, v199
	v_and_b32_e32 v233, 0xffff0000, v199
	v_lshlrev_b32_e32 v234, 16, v200
	v_and_b32_e32 v235, 0xffff0000, v200
	v_lshlrev_b32_e32 v236, 16, v201
	v_and_b32_e32 v237, 0xffff0000, v201
	v_mul_f32_e32 v62, v62, v230
	v_mul_f32_e32 v63, v63, v231
	v_mul_f32_e32 v64, v64, v232
	v_mul_f32_e32 v65, v65, v233
	v_mul_f32_e32 v58, v58, v234
	v_mul_f32_e32 v59, v59, v235
	v_mul_f32_e32 v60, v60, v236
	v_mul_f32_e32 v61, v61, v237
	v_cvt_pk_bf16_f32 v238, v62, v63
	v_cvt_pk_bf16_f32 v239, v64, v65
	v_cvt_pk_bf16_f32 v240, v58, v59
	v_cvt_pk_bf16_f32 v241, v60, v61
	global_store_dwordx4 v162, v[238:241], s[86:87]
	v_mul_f32_e32 v54, 0xbfb8aa3b, v54
	v_mul_f32_e32 v55, 0xbfb8aa3b, v55
	v_mul_f32_e32 v56, 0xbfb8aa3b, v56
	v_mul_f32_e32 v57, 0xbfb8aa3b, v57
	v_mul_f32_e32 v50, 0xbfb8aa3b, v50
	v_mul_f32_e32 v51, 0xbfb8aa3b, v51
	v_mul_f32_e32 v52, 0xbfb8aa3b, v52
	v_mul_f32_e32 v53, 0xbfb8aa3b, v53
	v_exp_f32_e32 v54, v54
	v_exp_f32_e32 v55, v55
	v_exp_f32_e32 v56, v56
	v_exp_f32_e32 v57, v57
	v_exp_f32_e32 v50, v50
	v_exp_f32_e32 v51, v51
	v_exp_f32_e32 v52, v52
	v_exp_f32_e32 v53, v53
	v_add_f32_e32 v54, 1.0, v54
	v_add_f32_e32 v55, 1.0, v55
	v_add_f32_e32 v56, 1.0, v56
	v_add_f32_e32 v57, 1.0, v57
	v_add_f32_e32 v50, 1.0, v50
	v_add_f32_e32 v51, 1.0, v51
	v_add_f32_e32 v52, 1.0, v52
	v_add_f32_e32 v53, 1.0, v53
	v_rcp_f32_e32 v54, v54
	v_rcp_f32_e32 v55, v55
	v_rcp_f32_e32 v56, v56
	v_rcp_f32_e32 v57, v57
	v_rcp_f32_e32 v50, v50
	v_rcp_f32_e32 v51, v51
	v_rcp_f32_e32 v52, v52
	v_rcp_f32_e32 v53, v53
	s_waitcnt vmcnt(15)
	v_lshlrev_b32_e32 v230, 16, v202
	v_and_b32_e32 v231, 0xffff0000, v202
	v_lshlrev_b32_e32 v232, 16, v203
	v_and_b32_e32 v233, 0xffff0000, v203
	v_lshlrev_b32_e32 v234, 16, v204
	v_and_b32_e32 v235, 0xffff0000, v204
	v_lshlrev_b32_e32 v236, 16, v205
	v_and_b32_e32 v237, 0xffff0000, v205
	v_mul_f32_e32 v54, v54, v230
	v_mul_f32_e32 v55, v55, v231
	v_mul_f32_e32 v56, v56, v232
	v_mul_f32_e32 v57, v57, v233
	v_mul_f32_e32 v50, v50, v234
	v_mul_f32_e32 v51, v51, v235
	v_mul_f32_e32 v52, v52, v236
	v_mul_f32_e32 v53, v53, v237
	v_cvt_pk_bf16_f32 v238, v54, v55
	v_cvt_pk_bf16_f32 v239, v56, v57
	v_cvt_pk_bf16_f32 v240, v50, v51
	v_cvt_pk_bf16_f32 v241, v52, v53
	global_store_dwordx4 v162, v[238:241], s[86:87] offset:256
	v_mul_f32_e32 v46, 0xbfb8aa3b, v46
	v_mul_f32_e32 v47, 0xbfb8aa3b, v47
	v_mul_f32_e32 v48, 0xbfb8aa3b, v48
	v_mul_f32_e32 v49, 0xbfb8aa3b, v49
	v_mul_f32_e32 v42, 0xbfb8aa3b, v42
	v_mul_f32_e32 v43, 0xbfb8aa3b, v43
	v_mul_f32_e32 v44, 0xbfb8aa3b, v44
	v_mul_f32_e32 v45, 0xbfb8aa3b, v45
	v_exp_f32_e32 v46, v46
	v_exp_f32_e32 v47, v47
	v_exp_f32_e32 v48, v48
	v_exp_f32_e32 v49, v49
	v_exp_f32_e32 v42, v42
	v_exp_f32_e32 v43, v43
	v_exp_f32_e32 v44, v44
	v_exp_f32_e32 v45, v45
	v_add_f32_e32 v46, 1.0, v46
	v_add_f32_e32 v47, 1.0, v47
	v_add_f32_e32 v48, 1.0, v48
	v_add_f32_e32 v49, 1.0, v49
	v_add_f32_e32 v42, 1.0, v42
	v_add_f32_e32 v43, 1.0, v43
	v_add_f32_e32 v44, 1.0, v44
	v_add_f32_e32 v45, 1.0, v45
	v_rcp_f32_e32 v46, v46
	v_rcp_f32_e32 v47, v47
	v_rcp_f32_e32 v48, v48
	v_rcp_f32_e32 v49, v49
	v_rcp_f32_e32 v42, v42
	v_rcp_f32_e32 v43, v43
	v_rcp_f32_e32 v44, v44
	v_rcp_f32_e32 v45, v45
	s_waitcnt vmcnt(15)
	v_lshlrev_b32_e32 v230, 16, v206
	v_and_b32_e32 v231, 0xffff0000, v206
	v_lshlrev_b32_e32 v232, 16, v207
	v_and_b32_e32 v233, 0xffff0000, v207
	v_lshlrev_b32_e32 v234, 16, v208
	v_and_b32_e32 v235, 0xffff0000, v208
	v_lshlrev_b32_e32 v236, 16, v209
	v_and_b32_e32 v237, 0xffff0000, v209
	v_mul_f32_e32 v46, v46, v230
	v_mul_f32_e32 v47, v47, v231
	v_mul_f32_e32 v48, v48, v232
	v_mul_f32_e32 v49, v49, v233
	v_mul_f32_e32 v42, v42, v234
	v_mul_f32_e32 v43, v43, v235
	v_mul_f32_e32 v44, v44, v236
	v_mul_f32_e32 v45, v45, v237
	v_cvt_pk_bf16_f32 v238, v46, v47
	v_cvt_pk_bf16_f32 v239, v48, v49
	v_cvt_pk_bf16_f32 v240, v42, v43
	v_cvt_pk_bf16_f32 v241, v44, v45
	global_store_dwordx4 v163, v[238:241], s[86:87]
	v_mul_f32_e32 v38, 0xbfb8aa3b, v38
	v_mul_f32_e32 v39, 0xbfb8aa3b, v39
	v_mul_f32_e32 v40, 0xbfb8aa3b, v40
	v_mul_f32_e32 v41, 0xbfb8aa3b, v41
	v_mul_f32_e32 v34, 0xbfb8aa3b, v34
	v_mul_f32_e32 v35, 0xbfb8aa3b, v35
	v_mul_f32_e32 v36, 0xbfb8aa3b, v36
	v_mul_f32_e32 v37, 0xbfb8aa3b, v37
	v_exp_f32_e32 v38, v38
	v_exp_f32_e32 v39, v39
	v_exp_f32_e32 v40, v40
	v_exp_f32_e32 v41, v41
	v_exp_f32_e32 v34, v34
	v_exp_f32_e32 v35, v35
	v_exp_f32_e32 v36, v36
	v_exp_f32_e32 v37, v37
	v_add_f32_e32 v38, 1.0, v38
	v_add_f32_e32 v39, 1.0, v39
	v_add_f32_e32 v40, 1.0, v40
	v_add_f32_e32 v41, 1.0, v41
	v_add_f32_e32 v34, 1.0, v34
	v_add_f32_e32 v35, 1.0, v35
	v_add_f32_e32 v36, 1.0, v36
	v_add_f32_e32 v37, 1.0, v37
	v_rcp_f32_e32 v38, v38
	v_rcp_f32_e32 v39, v39
	v_rcp_f32_e32 v40, v40
	v_rcp_f32_e32 v41, v41
	v_rcp_f32_e32 v34, v34
	v_rcp_f32_e32 v35, v35
	v_rcp_f32_e32 v36, v36
	v_rcp_f32_e32 v37, v37
	s_waitcnt vmcnt(15)
; __device__ __forceinline__ unsigned cvt_pk_bf16(float lo, float hi) { unsigned r; asm volatile("v_cvt_pk_bf16_f32 %0, %1, %2" : "=v"(r) : "v"(lo), "v"(hi)); return r; }
; __device__ __forceinline__ f32x4 sigm4(f32x4 v) { return (f32x4){sigm(v[0]), sigm(v[1]), sigm(v[2]), sigm(v[3])}; }
; __device__ __forceinline__ void unpack8(u32x4 w, f32x4& lo, f32x4& hi) { lo = (f32x4){bfl(w.x), bfh(w.x), bfl(w.y), bfh(w.y)}; hi = (f32x4){bfl(w.z), bfh(w.z), bfl(w.w), bfh(w.w)}; }
; __device__ __forceinline__ float sigm(float x) { return __builtin_amdgcn_rcpf(1.0f + __expf(-x)); }
;     __device__ __forceinline__ void operator()(const f32x4 (&acc)[2][2][4][2], const Unit& u, int wr, int wc, int fr, int fq) const {
;     ...
;             for (int m = 0; m < 4; ++m) { const size_t ro = (size_t)(row0 + ai * HALF + m * 16) * D + col0;
; #pragma unroll
;                 for (int bj = 0; bj < 2; ++bj) { const u32x4 pw = *(const u32x4*)(PUP + ro + bj * HALF); f32x4 p0, p1; unpack8(pw, p0, p1);
;                     const f32x4 v0 = sigm4(acc[ai][bj][m][0]) * p0, v1 = sigm4(acc[ai][bj][m][1]) * p1;
;                     u32x4 w; w.x = cvt_pk_bf16(v0[0], v0[1]); w.y = cvt_pk_bf16(v0[2], v0[3]); w.z = cvt_pk_bf16(v1[0], v1[1]); w.w = cvt_pk_bf16(v1[2], v1[3]);
;                     *(u32x4*)(T + ro + bj * HALF) = w; }
	v_lshlrev_b32_e32 v230, 16, v210
	v_and_b32_e32 v231, 0xffff0000, v210
	v_lshlrev_b32_e32 v232, 16, v211
	v_and_b32_e32 v233, 0xffff0000, v211
	v_lshlrev_b32_e32 v234, 16, v212
	v_and_b32_e32 v235, 0xffff0000, v212
	v_lshlrev_b32_e32 v236, 16, v213
	v_and_b32_e32 v237, 0xffff0000, v213
	v_mul_f32_e32 v38, v38, v230
	v_mul_f32_e32 v39, v39, v231
	v_mul_f32_e32 v40, v40, v232
	v_mul_f32_e32 v41, v41, v233
	v_mul_f32_e32 v34, v34, v234
	v_mul_f32_e32 v35, v35, v235
	v_mul_f32_e32 v36, v36, v236
	v_mul_f32_e32 v37, v37, v237
	v_cvt_pk_bf16_f32 v238, v38, v39
	v_cvt_pk_bf16_f32 v239, v40, v41
	v_cvt_pk_bf16_f32 v240, v34, v35
	v_cvt_pk_bf16_f32 v241, v36, v37
	global_store_dwordx4 v163, v[238:241], s[86:87] offset:256
	v_mul_f32_e32 v30, 0xbfb8aa3b, v30
	v_mul_f32_e32 v31, 0xbfb8aa3b, v31
	v_mul_f32_e32 v32, 0xbfb8aa3b, v32
	v_mul_f32_e32 v33, 0xbfb8aa3b, v33
	v_mul_f32_e32 v26, 0xbfb8aa3b, v26
	v_mul_f32_e32 v27, 0xbfb8aa3b, v27
	v_mul_f32_e32 v28, 0xbfb8aa3b, v28
	v_mul_f32_e32 v29, 0xbfb8aa3b, v29
	v_exp_f32_e32 v30, v30
	v_exp_f32_e32 v31, v31
	v_exp_f32_e32 v32, v32
	v_exp_f32_e32 v33, v33
	v_exp_f32_e32 v26, v26
	v_exp_f32_e32 v27, v27
	v_exp_f32_e32 v28, v28
	v_exp_f32_e32 v29, v29
	v_add_f32_e32 v30, 1.0, v30
	v_add_f32_e32 v31, 1.0, v31
	v_add_f32_e32 v32, 1.0, v32
	v_add_f32_e32 v33, 1.0, v33
	v_add_f32_e32 v26, 1.0, v26
	v_add_f32_e32 v27, 1.0, v27
	v_add_f32_e32 v28, 1.0, v28
	v_add_f32_e32 v29, 1.0, v29
	v_rcp_f32_e32 v30, v30
	v_rcp_f32_e32 v31, v31
	v_rcp_f32_e32 v32, v32
	v_rcp_f32_e32 v33, v33
	v_rcp_f32_e32 v26, v26
	v_rcp_f32_e32 v27, v27
	v_rcp_f32_e32 v28, v28
	v_rcp_f32_e32 v29, v29
	s_waitcnt vmcnt(15)
	v_lshlrev_b32_e32 v230, 16, v214
	v_and_b32_e32 v231, 0xffff0000, v214
	v_lshlrev_b32_e32 v232, 16, v215
	v_and_b32_e32 v233, 0xffff0000, v215
	v_lshlrev_b32_e32 v234, 16, v216
	v_and_b32_e32 v235, 0xffff0000, v216
	v_lshlrev_b32_e32 v236, 16, v217
	v_and_b32_e32 v237, 0xffff0000, v217
	v_mul_f32_e32 v30, v30, v230
	v_mul_f32_e32 v31, v31, v231
	v_mul_f32_e32 v32, v32, v232
	v_mul_f32_e32 v33, v33, v233
	v_mul_f32_e32 v26, v26, v234
	v_mul_f32_e32 v27, v27, v235
	v_mul_f32_e32 v28, v28, v236
	v_mul_f32_e32 v29, v29, v237
	v_cvt_pk_bf16_f32 v238, v30, v31
	v_cvt_pk_bf16_f32 v239, v32, v33
	v_cvt_pk_bf16_f32 v240, v26, v27
	v_cvt_pk_bf16_f32 v241, v28, v29
	global_store_dwordx4 v164, v[238:241], s[86:87]
	v_mul_f32_e32 v22, 0xbfb8aa3b, v22
	v_mul_f32_e32 v23, 0xbfb8aa3b, v23
	v_mul_f32_e32 v24, 0xbfb8aa3b, v24
	v_mul_f32_e32 v25, 0xbfb8aa3b, v25
	v_mul_f32_e32 v18, 0xbfb8aa3b, v18
	v_mul_f32_e32 v19, 0xbfb8aa3b, v19
	v_mul_f32_e32 v20, 0xbfb8aa3b, v20
	v_mul_f32_e32 v21, 0xbfb8aa3b, v21
	v_exp_f32_e32 v22, v22
	v_exp_f32_e32 v23, v23
	v_exp_f32_e32 v24, v24
	v_exp_f32_e32 v25, v25
	v_exp_f32_e32 v18, v18
	v_exp_f32_e32 v19, v19
	v_exp_f32_e32 v20, v20
	v_exp_f32_e32 v21, v21
	v_add_f32_e32 v22, 1.0, v22
	v_add_f32_e32 v23, 1.0, v23
	v_add_f32_e32 v24, 1.0, v24
	v_add_f32_e32 v25, 1.0, v25
	v_add_f32_e32 v18, 1.0, v18
	v_add_f32_e32 v19, 1.0, v19
	v_add_f32_e32 v20, 1.0, v20
	v_add_f32_e32 v21, 1.0, v21
	v_rcp_f32_e32 v22, v22
	v_rcp_f32_e32 v23, v23
	v_rcp_f32_e32 v24, v24
	v_rcp_f32_e32 v25, v25
	v_rcp_f32_e32 v18, v18
	v_rcp_f32_e32 v19, v19
	v_rcp_f32_e32 v20, v20
	v_rcp_f32_e32 v21, v21
	s_waitcnt vmcnt(15)
; __device__ __forceinline__ unsigned cvt_pk_bf16(float lo, float hi) { unsigned r; asm volatile("v_cvt_pk_bf16_f32 %0, %1, %2" : "=v"(r) : "v"(lo), "v"(hi)); return r; }
; __device__ __forceinline__ f32x4 sigm4(f32x4 v) { return (f32x4){sigm(v[0]), sigm(v[1]), sigm(v[2]), sigm(v[3])}; }
; __device__ __forceinline__ void unpack8(u32x4 w, f32x4& lo, f32x4& hi) { lo = (f32x4){bfl(w.x), bfh(w.x), bfl(w.y), bfh(w.y)}; hi = (f32x4){bfl(w.z), bfh(w.z), bfl(w.w), bfh(w.w)}; }
;     __device__ __forceinline__ void operator()(const f32x4 (&acc)[2][2][4][2], const Unit& u, int wr, int wc, int fr, int fq) const {
;     ...
;             for (int m = 0; m < 4; ++m) { const size_t ro = (size_t)(row0 + ai * HALF + m * 16) * D + col0;
; #pragma unroll
;                 for (int bj = 0; bj < 2; ++bj) { const u32x4 pw = *(const u32x4*)(PUP + ro + bj * HALF); f32x4 p0, p1; unpack8(pw, p0, p1);
;                     const f32x4 v0 = sigm4(acc[ai][bj][m][0]) * p0, v1 = sigm4(acc[ai][bj][m][1]) * p1;
;                     u32x4 w; w.x = cvt_pk_bf16(v0[0], v0[1]); w.y = cvt_pk_bf16(v0[2], v0[3]); w.z = cvt_pk_bf16(v1[0], v1[1]); w.w = cvt_pk_bf16(v1[2], v1[3]);
;                     *(u32x4*)(T + ro + bj * HALF) = w; }
;                 asm volatile("" ::: "memory"); }
	v_lshlrev_b32_e32 v230, 16, v218
	v_and_b32_e32 v231, 0xffff0000, v218
	v_lshlrev_b32_e32 v232, 16, v219
	v_and_b32_e32 v233, 0xffff0000, v219
	v_lshlrev_b32_e32 v234, 16, v220
	v_and_b32_e32 v235, 0xffff0000, v220
	v_lshlrev_b32_e32 v236, 16, v221
	v_and_b32_e32 v237, 0xffff0000, v221
	v_mul_f32_e32 v22, v22, v230
	v_mul_f32_e32 v23, v23, v231
	v_mul_f32_e32 v24, v24, v232
	v_mul_f32_e32 v25, v25, v233
	v_mul_f32_e32 v18, v18, v234
	v_mul_f32_e32 v19, v19, v235
	v_mul_f32_e32 v20, v20, v236
	v_mul_f32_e32 v21, v21, v237
	v_cvt_pk_bf16_f32 v238, v22, v23
	v_cvt_pk_bf16_f32 v239, v24, v25
	v_cvt_pk_bf16_f32 v240, v18, v19
	v_cvt_pk_bf16_f32 v241, v20, v21
	global_store_dwordx4 v164, v[238:241], s[86:87] offset:256
	v_mul_f32_e32 v14, 0xbfb8aa3b, v14
	v_mul_f32_e32 v15, 0xbfb8aa3b, v15
	v_mul_f32_e32 v16, 0xbfb8aa3b, v16
	v_mul_f32_e32 v17, 0xbfb8aa3b, v17
	v_mul_f32_e32 v10, 0xbfb8aa3b, v10
	v_mul_f32_e32 v11, 0xbfb8aa3b, v11
	v_mul_f32_e32 v12, 0xbfb8aa3b, v12
	v_mul_f32_e32 v13, 0xbfb8aa3b, v13
	v_exp_f32_e32 v14, v14
	v_exp_f32_e32 v15, v15
	v_exp_f32_e32 v16, v16
	v_exp_f32_e32 v17, v17
	v_exp_f32_e32 v10, v10
	v_exp_f32_e32 v11, v11
	v_exp_f32_e32 v12, v12
	v_exp_f32_e32 v13, v13
	v_add_f32_e32 v14, 1.0, v14
	v_add_f32_e32 v15, 1.0, v15
	v_add_f32_e32 v16, 1.0, v16
	v_add_f32_e32 v17, 1.0, v17
	v_add_f32_e32 v10, 1.0, v10
	v_add_f32_e32 v11, 1.0, v11
	v_add_f32_e32 v12, 1.0, v12
	v_add_f32_e32 v13, 1.0, v13
	v_rcp_f32_e32 v14, v14
	v_rcp_f32_e32 v15, v15
	v_rcp_f32_e32 v16, v16
	v_rcp_f32_e32 v17, v17
	v_rcp_f32_e32 v10, v10
	v_rcp_f32_e32 v11, v11
	v_rcp_f32_e32 v12, v12
	v_rcp_f32_e32 v13, v13
	s_waitcnt vmcnt(15)
	v_lshlrev_b32_e32 v230, 16, v222
	v_and_b32_e32 v231, 0xffff0000, v222
	v_lshlrev_b32_e32 v232, 16, v223
	v_and_b32_e32 v233, 0xffff0000, v223
	v_lshlrev_b32_e32 v234, 16, v224
	v_and_b32_e32 v235, 0xffff0000, v224
	v_lshlrev_b32_e32 v236, 16, v225
	v_and_b32_e32 v237, 0xffff0000, v225
	v_mul_f32_e32 v14, v14, v230
	v_mul_f32_e32 v15, v15, v231
	v_mul_f32_e32 v16, v16, v232
	v_mul_f32_e32 v17, v17, v233
	v_mul_f32_e32 v10, v10, v234
	v_mul_f32_e32 v11, v11, v235
	v_mul_f32_e32 v12, v12, v236
	v_mul_f32_e32 v13, v13, v237
	v_cvt_pk_bf16_f32 v238, v14, v15
	v_cvt_pk_bf16_f32 v239, v16, v17
	v_cvt_pk_bf16_f32 v240, v10, v11
	v_cvt_pk_bf16_f32 v241, v12, v13
	global_store_dwordx4 v165, v[238:241], s[86:87]
	v_mul_f32_e32 v6, 0xbfb8aa3b, v6
	v_mul_f32_e32 v7, 0xbfb8aa3b, v7
	v_mul_f32_e32 v8, 0xbfb8aa3b, v8
	v_mul_f32_e32 v9, 0xbfb8aa3b, v9
	v_mul_f32_e32 v2, 0xbfb8aa3b, v2
	v_mul_f32_e32 v3, 0xbfb8aa3b, v3
	v_mul_f32_e32 v4, 0xbfb8aa3b, v4
	v_mul_f32_e32 v5, 0xbfb8aa3b, v5
	v_exp_f32_e32 v6, v6
	v_exp_f32_e32 v7, v7
	v_exp_f32_e32 v8, v8
	v_exp_f32_e32 v9, v9
	v_exp_f32_e32 v2, v2
	v_exp_f32_e32 v3, v3
	v_exp_f32_e32 v4, v4
	v_exp_f32_e32 v5, v5
	v_add_f32_e32 v6, 1.0, v6
	v_add_f32_e32 v7, 1.0, v7
	v_add_f32_e32 v8, 1.0, v8
	v_add_f32_e32 v9, 1.0, v9
	v_add_f32_e32 v2, 1.0, v2
	v_add_f32_e32 v3, 1.0, v3
	v_add_f32_e32 v4, 1.0, v4
	v_add_f32_e32 v5, 1.0, v5
	v_rcp_f32_e32 v6, v6
	v_rcp_f32_e32 v7, v7
	v_rcp_f32_e32 v8, v8
	v_rcp_f32_e32 v9, v9
	v_rcp_f32_e32 v2, v2
	v_rcp_f32_e32 v3, v3
	v_rcp_f32_e32 v4, v4
	v_rcp_f32_e32 v5, v5
	s_waitcnt vmcnt(15)
	v_lshlrev_b32_e32 v230, 16, v226
	v_and_b32_e32 v231, 0xffff0000, v226
	v_lshlrev_b32_e32 v232, 16, v227
	v_and_b32_e32 v233, 0xffff0000, v227
	v_lshlrev_b32_e32 v234, 16, v228
	v_and_b32_e32 v235, 0xffff0000, v228
	v_lshlrev_b32_e32 v236, 16, v229
	v_and_b32_e32 v237, 0xffff0000, v229
	v_mul_f32_e32 v6, v6, v230
	v_mul_f32_e32 v7, v7, v231
	v_mul_f32_e32 v8, v8, v232
	v_mul_f32_e32 v9, v9, v233
	v_mul_f32_e32 v2, v2, v234
	v_mul_f32_e32 v3, v3, v235
	v_mul_f32_e32 v4, v4, v236
	v_mul_f32_e32 v5, v5, v237
	v_cvt_pk_bf16_f32 v238, v6, v7
	v_cvt_pk_bf16_f32 v239, v8, v9
	v_cvt_pk_bf16_f32 v240, v2, v3
	v_cvt_pk_bf16_f32 v241, v4, v5
	global_store_dwordx4 v165, v[238:241], s[86:87] offset:256
	s_cbranch_vccnz .LBB0_1812
	s_andn2_b64 vcc, exec, s[8:9]
	s_cbranch_vccnz .LBB0_1811
	s_barrier
	s_branch .LBB0_1811
